# P0 x->bf16 row loop: the wait for the first row load sat after 10 of the 16 loads (stalling the other 6 behind a full HBM latency); moved after all 16 loads are issued
# speedup vs baseline: 1.0063x; 1.0063x over previous
; __device__ __forceinline__ unsigned pk2(float lo, float hi) { f32x2_t v = {lo, hi}; bf16x2_t b = __builtin_convertvector(v, bf16x2_t); return __builtin_bit_cast(unsigned, b); }
; __global__ void __launch_bounds__(512, 2) mega(Args a) {
;     ...
;         for (int row = gw; row < S; row += 2 * NGW) {
;             const int row2 = row + NGW;
;             const bool has2 = row2 < S;
;             const f32x4* xr = (const f32x4*)(x + (size_t)row * 2048) + lane; const f32x4* xr2 = (const f32x4*)(x + (size_t)(has2 ? row2 : row) * 2048) + lane;
;             f32x4 v[8], v2[8]; float s = 0.f, s2 = 0.f;
; #pragma unroll
;             for (int j = 0; j < 8; ++j) { v[j] = __builtin_nontemporal_load(xr + 64 * j); v2[j] = __builtin_nontemporal_load(xr2 + 64 * j); }
; #pragma unroll
;             for (int j = 0; j < 8; ++j) { s += (v[j][0] * v[j][0] + v[j][1] * v[j][1]) + (v[j][2] * v[j][2] + v[j][3] * v[j][3]); s2 += (v2[j][0] * v2[j][0] + v2[j][1] * v2[j][1]) + (v2[j][2] * v2[j][2] + v2[j][3] * v2[j][3]); }
;             s = wave_sum(s); s2 = wave_sum(s2);
;             u32x2* o8 = (u32x2*)(XB + (size_t)row * 2048) + lane;
; #pragma unroll
;             for (int j = 0; j < 8; ++j) { u32x2 w; w.x = pk2(v[j][0], v[j][1]); w.y = pk2(v[j][2], v[j][3]); o8[64 * j] = w; }
;             if (lane == 0) { R1[row] = rsqrtf(s * (1.f / 2048.f) + EPS); SS2[row] = 0.f; SS3[row] = 0.f; if (row < 64) { ((unsigned*)(ws + WS_CNT))[64 * row] = 0u; ((unsigned*)(ws + WS_CNT))[64 * 64 + 64 * row] = 0u; } }
.LBB0_210:
	s_add_i32 s3, s42, s36
	s_cmpk_lt_i32 s3, 0x4000
	s_cselect_b64 s[24:25], -1, 0
	s_and_b64 s[26:27], s[24:25], exec
	global_load_dwordx4 v[76:79], v[56:57], off offset:-4096 nt
	global_load_dwordx4 v[48:51], v[56:57], off offset:-3072 nt
	global_load_dwordx4 v[44:47], v[56:57], off offset:-2048 nt
	global_load_dwordx4 v[40:43], v[56:57], off offset:-1024 nt
	global_load_dwordx4 v[32:35], v[56:57], off nt
	global_load_dwordx4 v[36:39], v[56:57], off offset:1024 nt
	s_cselect_b32 s26, s3, s36
	s_ashr_i32 s27, s26, 31
	s_lshl_b64 s[26:27], s[26:27], 13
	v_lshl_add_u64 v[0:1], v[54:55], 0, s[26:27]
	global_load_dwordx4 v[28:31], v[0:1], off nt
	global_load_dwordx4 v[24:27], v[0:1], off offset:1024 nt
	global_load_dwordx4 v[20:23], v[0:1], off offset:2048 nt
	global_load_dwordx4 v[16:19], v[0:1], off offset:3072 nt
	v_add_co_u32_e32 v0, vcc, s1, v0
	v_addc_co_u32_e32 v1, vcc, 0, v1, vcc
	global_load_dwordx4 v[12:15], v[0:1], off nt
	global_load_dwordx4 v[8:11], v[0:1], off offset:1024 nt
	global_load_dwordx4 v[80:83], v[56:57], off offset:2048 nt
	global_load_dwordx4 v[4:7], v[0:1], off offset:2048 nt
	global_load_dwordx4 v[84:87], v[56:57], off offset:3072 nt
	s_nop 0
	global_load_dwordx4 v[0:3], v[0:1], off offset:3072 nt
	s_waitcnt vmcnt(15)
	v_mul_f32_e32 v71, v77, v77
	s_waitcnt lgkmcnt(0)
	v_mul_f32_e32 v72, v79, v79
	s_waitcnt vmcnt(14)
	v_mul_f32_e32 v73, v49, v49
	v_mul_f32_e32 v74, v51, v51
	s_waitcnt vmcnt(13)
	v_mul_f32_e32 v75, v45, v45
	v_mul_f32_e32 v88, v47, v47
	v_fmac_f32_e32 v71, v76, v76
	v_fmac_f32_e32 v72, v78, v78
	v_fmac_f32_e32 v73, v48, v48
	v_fmac_f32_e32 v74, v50, v50
	s_waitcnt vmcnt(12)
	v_mul_f32_e32 v89, v41, v41
	v_mul_f32_e32 v90, v43, v43
	v_fmac_f32_e32 v75, v44, v44
	v_fmac_f32_e32 v88, v46, v46
	v_add_f32_e32 v71, v71, v72
	v_add_f32_e32 v72, v73, v74
	s_waitcnt vmcnt(11)
	v_mul_f32_e32 v91, v33, v33
	v_mul_f32_e32 v92, v35, v35
	v_fmac_f32_e32 v89, v40, v40
	v_fmac_f32_e32 v90, v42, v42
	v_add_f32_e32 v73, v75, v88
	v_add_f32_e32 v71, v71, v72
	s_waitcnt vmcnt(10)
	v_mul_f32_e32 v93, v37, v37
	v_mul_f32_e32 v94, v39, v39
	v_fmac_f32_e32 v91, v32, v32
	v_fmac_f32_e32 v92, v34, v34
	v_add_f32_e32 v74, v89, v90
	v_add_f32_e32 v71, v71, v73
	v_fmac_f32_e32 v93, v36, v36
	v_fmac_f32_e32 v94, v38, v38
	v_add_f32_e32 v75, v91, v92
	v_add_f32_e32 v71, v71, v74
	v_add_f32_e32 v88, v93, v94
	v_add_f32_e32 v71, v71, v75
	s_waitcnt vmcnt(9)
	v_mul_f32_e32 v72, v29, v29
	v_mul_f32_e32 v73, v31, v31
	s_waitcnt vmcnt(8)
	v_mul_f32_e32 v74, v25, v25
	v_mul_f32_e32 v75, v27, v27
	v_add_f32_e32 v71, v71, v88
	s_waitcnt vmcnt(7)
	v_mul_f32_e32 v88, v21, v21
	v_mul_f32_e32 v89, v23, v23
	v_fmac_f32_e32 v72, v28, v28
	v_fmac_f32_e32 v73, v30, v30
	v_fmac_f32_e32 v74, v24, v24
	v_fmac_f32_e32 v75, v26, v26
	s_waitcnt vmcnt(6)
	v_mul_f32_e32 v90, v17, v17
	v_mul_f32_e32 v91, v19, v19
	v_fmac_f32_e32 v88, v20, v20
	v_fmac_f32_e32 v89, v22, v22
	v_add_f32_e32 v72, v72, v73
	v_add_f32_e32 v73, v74, v75
	v_fmac_f32_e32 v90, v16, v16
	v_fmac_f32_e32 v91, v18, v18
	v_add_f32_e32 v74, v88, v89
	v_add_f32_e32 v72, v72, v73
	v_add_f32_e32 v75, v90, v91
	v_add_f32_e32 v72, v72, v74
	v_add_f32_e32 v72, v72, v75
	v_lshl_add_u64 v[88:89], s[88:89], 0, v[60:61]
	v_cvt_pk_bf16_f32 v76, v76, v77
	v_cvt_pk_bf16_f32 v77, v78, v79
	v_add_co_u32_e32 v78, vcc, s34, v88
	v_cvt_pk_bf16_f32 v32, v32, v33
	s_nop 0
	v_addc_co_u32_e32 v79, vcc, 0, v89, vcc
	v_cvt_pk_bf16_f32 v33, v34, v35
	global_store_dwordx2 v[78:79], v[32:33], off offset:2048
	v_cvt_pk_bf16_f32 v32, v36, v37
	v_cvt_pk_bf16_f32 v33, v38, v39
	global_store_dwordx2 v[78:79], v[32:33], off offset:2560
	v_cvt_pk_bf16_f32 v48, v48, v49
	v_cvt_pk_bf16_f32 v49, v50, v51
	v_cvt_pk_bf16_f32 v44, v44, v45
	v_cvt_pk_bf16_f32 v45, v46, v47
	s_waitcnt vmcnt(7)
	v_mul_f32_e32 v92, v13, v13
	v_mul_f32_e32 v93, v15, v15
	s_waitcnt vmcnt(6)
	v_mul_f32_e32 v94, v9, v9
	v_mul_f32_e32 v95, v11, v11
	v_fmac_f32_e32 v92, v12, v12
	v_fmac_f32_e32 v93, v14, v14
	v_fmac_f32_e32 v94, v8, v8
	v_add_f32_e32 v73, v92, v93
	v_fmac_f32_e32 v95, v10, v10
	v_add_f32_e32 v72, v72, v73
	v_add_f32_e32 v73, v94, v95
	v_add_f32_e32 v72, v72, v73
	s_waitcnt vmcnt(5)
	v_mul_f32_e32 v73, v81, v81
	v_mul_f32_e32 v74, v83, v83
	v_fmac_f32_e32 v73, v80, v80
	v_fmac_f32_e32 v74, v82, v82
	v_add_f32_e32 v73, v73, v74
	v_add_f32_e32 v71, v71, v73
	s_waitcnt vmcnt(4)
	v_mul_f32_e32 v73, v5, v5
	v_mul_f32_e32 v74, v7, v7
	v_fmac_f32_e32 v73, v4, v4
	v_fmac_f32_e32 v74, v6, v6
	v_add_f32_e32 v73, v73, v74
	v_add_f32_e32 v72, v72, v73
	s_waitcnt vmcnt(3)
	v_mul_f32_e32 v73, v85, v85
	v_mul_f32_e32 v74, v87, v87
	v_fmac_f32_e32 v73, v84, v84
	v_fmac_f32_e32 v74, v86, v86
	v_add_f32_e32 v73, v73, v74
	v_add_f32_e32 v71, v71, v73
	s_waitcnt vmcnt(2)
	v_mul_f32_e32 v73, v1, v1
	v_mul_f32_e32 v74, v3, v3
	v_fmac_f32_e32 v73, v0, v0
	v_fmac_f32_e32 v74, v2, v2
	v_add_f32_e32 v73, v73, v74
	v_add_f32_e32 v72, v72, v73
	ds_bpermute_b32 v74, v62, v71
	ds_bpermute_b32 v73, v62, v72
	v_cvt_pk_bf16_f32 v32, v80, v81
	v_cvt_pk_bf16_f32 v33, v82, v83
	v_cvt_pk_bf16_f32 v40, v40, v41
	s_waitcnt lgkmcnt(1)
	v_add_f32_e32 v71, v71, v74
	s_waitcnt lgkmcnt(0)
	v_add_f32_e32 v72, v72, v73
	ds_bpermute_b32 v74, v63, v71
	ds_bpermute_b32 v73, v63, v72
	v_cvt_pk_bf16_f32 v41, v42, v43
	global_store_dwordx2 v[78:79], v[32:33], off offset:3072
	v_cvt_pk_bf16_f32 v32, v84, v85
	s_waitcnt lgkmcnt(1)
	v_add_f32_e32 v71, v71, v74
	s_waitcnt lgkmcnt(0)
	v_add_f32_e32 v72, v72, v73
	ds_bpermute_b32 v74, v64, v71
	ds_bpermute_b32 v73, v64, v72
	v_cvt_pk_bf16_f32 v33, v86, v87
	global_store_dwordx2 v[78:79], v[76:77], off
	global_store_dwordx2 v[78:79], v[48:49], off offset:512
	s_waitcnt lgkmcnt(1)
	v_add_f32_e32 v71, v71, v74
	s_waitcnt lgkmcnt(0)
	v_add_f32_e32 v72, v72, v73
	ds_bpermute_b32 v74, v65, v71
	ds_bpermute_b32 v73, v65, v72
	global_store_dwordx2 v[78:79], v[44:45], off offset:1024
	global_store_dwordx2 v[78:79], v[40:41], off offset:1536
	global_store_dwordx2 v[78:79], v[32:33], off offset:3584
	s_waitcnt lgkmcnt(1)
	v_add_f32_e32 v71, v71, v74
	s_waitcnt lgkmcnt(0)
	v_add_f32_e32 v72, v72, v73
	ds_bpermute_b32 v74, v66, v71
	ds_bpermute_b32 v75, v66, v72
	s_waitcnt lgkmcnt(1)
	v_add_f32_e32 v73, v71, v74
	s_waitcnt lgkmcnt(0)
	v_add_f32_e32 v71, v72, v75
	ds_bpermute_b32 v74, v67, v73
	ds_bpermute_b32 v72, v67, v71
	s_and_saveexec_b64 s[26:27], s[4:5]
	s_cbranch_execz .LBB0_213
; __device__ __forceinline__ unsigned pk2(float lo, float hi) { f32x2_t v = {lo, hi}; bf16x2_t b = __builtin_convertvector(v, bf16x2_t); return __builtin_bit_cast(unsigned, b); }
; __global__ void __launch_bounds__(512, 2) mega(Args a) {
;     ...
;             s = wave_sum(s); s2 = wave_sum(s2);
;             u32x2* o8 = (u32x2*)(XB + (size_t)row * 2048) + lane;
; #pragma unroll
;             for (int j = 0; j < 8; ++j) { u32x2 w; w.x = pk2(v[j][0], v[j][1]); w.y = pk2(v[j][2], v[j][3]); o8[64 * j] = w; }
;             if (lane == 0) { R1[row] = rsqrtf(s * (1.f / 2048.f) + EPS); SS2[row] = 0.f; SS3[row] = 0.f; if (row < 64) { ((unsigned*)(ws + WS_CNT))[64 * row] = 0u; ((unsigned*)(ws + WS_CNT))[64 * 64 + 64 * row] = 0u; } }
	s_waitcnt lgkmcnt(1)
	v_add_f32_e32 v32, v73, v74
	v_fmamk_f32 v32, v32, 0x3a000000, v52
	v_mul_f32_e32 v33, 0x4b800000, v32
	v_cmp_gt_f32_e32 vcc, s35, v32
	s_add_u32 s38, s88, s6
	s_addc_u32 s39, s89, s7
	v_cndmask_b32_e32 v32, v32, v33, vcc
	v_rsq_f32_e32 v32, v32
	s_cmp_gt_i32 s36, 63
	v_mul_f32_e32 v33, 0x45800000, v32
	v_cndmask_b32_e32 v32, v32, v33, vcc
	global_store_dword v68, v32, s[38:39]
	global_store_dword v53, v53, s[38:39]
	global_store_dword v69, v53, s[38:39]
	s_cbranch_scc1 .LBB0_213
	s_ashr_i32 s3, s2, 31
	s_lshl_b64 s[38:39], s[2:3], 2
	s_add_u32 s38, s30, s38
	s_addc_u32 s39, s31, s39
	global_store_dword v53, v53, s[38:39]
	global_store_dword v70, v53, s[38:39]
